# grid sync replaced: sharded 8-counter barrier in d_ws (dead regions), first sync stays cg
# speedup vs baseline: 1.0288x; 1.0288x over previous
; __device__ __forceinline__ int otid(int wv) { int l; asm volatile("v_mbcnt_lo_u32_b32 %0, -1, 0\n\tv_mbcnt_hi_u32_b32 %0, -1, %0" : "=v"(l)); return wv * 64 + l; }
; __device__ __forceinline__ KArgs kargs() { auto p = __builtin_amdgcn_kernarg_segment_ptr(); asm volatile("" : "+s"(p)); return (KArgs)p; }
; __global__ void __launch_bounds__(512, 2) mega(Args a_unused) {
;     ...
;     for (int ph = lo; ph < kargs()->hi; ++ph) {
;         KArgs ap = kargs();
;         const int G = gridDim.x, bx = blockIdx.x;
;         const int vcu = (G % 8 == 0) ? (bx % 8) * (G / 8) + bx / 8 : bx;
;         unsigned char* ws = ap->ws;
;         bf16_t* H = (bf16_t*)(ws + WS_H);
;         unsigned char* BIG = ws + WS_BIG;
;         float* MBUF = (float*)(ws + WS_MBUF);
;         const int tid = otid(wv), wid = __builtin_amdgcn_readfirstlane(tid >> 6), lane = tid & 63;
;         const int gw = vcu * 8 + wid, NGW = G * 8;
.LBB0_1:
	buffer_inv sc1
	s_waitcnt vmcnt(0)

; __device__ __forceinline__ KArgs kargs() { auto p = __builtin_amdgcn_kernarg_segment_ptr(); asm volatile("" : "+s"(p)); return (KArgs)p; }
; __global__ void __launch_bounds__(512, 2) mega(Args a_unused) {
;     ...
;         if (ph + 1 < kargs()->hi) { if (kargs()->coop) cg::this_grid().sync(); }
.LBB0_455:
	s_cmp_lt_u32 s88, 2
	s_cbranch_scc1 .Lgs_pre_slow
	s_load_dwordx2 s[6:7], s[82:83], 0xa0
	s_load_dword s1, s[82:83], 0xb8
	buffer_wbl2 sc1
	s_and_b32 s8, s80, 7
	s_lshl_b32 s8, s8, 8
	s_cmp_lt_u32 s88, 4
	s_cselect_b32 s9, 0x337ff000, 0
	s_cselect_b32 s10, 1, 3
	s_sub_u32 s10, s88, s10
	s_mov_b64 s[12:13], exec
	s_mov_b32 exec_lo, 0xff
	s_mov_b32 exec_hi, 0
	v_mbcnt_lo_u32_b32 v0, -1, 0
	s_waitcnt lgkmcnt(0)
	s_add_i32 s1, s1, 7
	v_sub_u32_e32 v2, s1, v0
	v_lshrrev_b32_e32 v2, 3, v2
	v_mul_lo_u32 v2, v2, s10
	v_lshlrev_b32_e32 v0, 8, v0
	s_cmp_eq_u32 s88, 3
	s_cbranch_scc0 .Lgs_noinit
	s_cmp_eq_u32 s80, 0
	s_cbranch_scc0 .Lgs_noinit
	global_store_dword v0, v211, s[6:7] sc0 sc1
.Lgs_noinit:
	s_add_u32 s6, s6, s9
	s_addc_u32 s7, s7, 0
	s_add_u32 s8, s6, s8
	s_addc_u32 s9, s7, 0
	s_mov_b64 exec, s[12:13]
	v_mov_b32_e32 v1, 1
	s_waitcnt vmcnt(0)
	global_atomic_add v211, v1, s[8:9]
	s_mov_b32 exec_lo, 0xff
	s_mov_b32 exec_hi, 0
.Lgs_poll:
	global_load_dword v1, v0, s[6:7] sc1
	s_waitcnt vmcnt(0)
	v_cmp_ge_u32_e32 vcc, v1, v2
	s_xor_b64 s[8:9], vcc, exec
	s_cmp_eq_u64 s[8:9], 0
	s_cbranch_scc1 .Lgs_done
	s_sleep 1
	s_branch .Lgs_poll
.Lgs_done:
	s_mov_b64 exec, s[12:13]
	s_branch .Lgs_join
.Lgs_pre_slow:
	s_cmp_lg_u32 s80, 0
	s_cbranch_scc1 .Lgs_slow
	s_load_dwordx2 s[6:7], s[82:83], 0xa0
	s_mov_b64 s[12:13], exec
	s_mov_b32 exec_lo, 0xff
	s_mov_b32 exec_hi, 0
	v_mbcnt_lo_u32_b32 v0, -1, 0
	v_lshlrev_b32_e32 v0, 8, v0
	s_waitcnt lgkmcnt(0)
	s_add_u32 s6, s6, 0x337ff000
	s_addc_u32 s7, s7, 0
	global_store_dword v0, v211, s[6:7] sc0 sc1
	s_waitcnt vmcnt(0)
	s_mov_b64 exec, s[12:13]

; __device__ __forceinline__ KArgs kargs() { auto p = __builtin_amdgcn_kernarg_segment_ptr(); asm volatile("" : "+s"(p)); return (KArgs)p; }
; __global__ void __launch_bounds__(512, 2) mega(Args a_unused) {
;     ...
;         if (ph + 1 < kargs()->hi) { if (kargs()->coop) cg::this_grid().sync(); }
.Lgs_join:
	s_getpc_b64 s[98:99]
